# P11: ln2 gamma/beta chunks 1..7 kept in registers (loaded once), output stores no longer wait for the previous store's ack
# speedup vs baseline: 1.0022x; 1.0022x over previous
; DEVINL int otid() { int t = threadIdx.x; asm volatile("" : "+v"(t)); return t; }
; DEVINL void phase11(const Params& p) {
;   const int tid = otid();
;   const int lane = tid & 63;
;   const int gw = blockIdx.x * 8 + (tid >> 6), nw = gridDim.x * 8;
;   for (int row = gw; row < T_; row += nw) {
;     const u16* hb = (const u16*)(p.ws + O_HBF) + (long)row * 2048;
;     ...
;     for (int i = 0; i < 8; ++i) sum += v[i].x + v[i].y + v[i].z + v[i].w;
;     const float mu = allred64(sum) * (1.f / 2048.f);
;     float sq = 0.f;
; #pragma unroll
;     for (int i = 0; i < 8; ++i) {
;       v[i].x -= mu; v[i].y -= mu; v[i].z -= mu; v[i].w -= mu;
;       sq += v[i].x * v[i].x + v[i].y * v[i].y + v[i].z * v[i].z + v[i].w * v[i].w;
;     }
;     const float rstd = rsqrtf(allred64(sq) * (1.f / 2048.f) + 1e-5f);
; #pragma unroll
;     for (int i = 0; i < 8; ++i) {
;       const int c = i * 256 + lane * 4;
;       float4 gq = *(const float4*)(p.ln2_g + c);
;       float4 bq = *(const float4*)(p.ln2_b + c);
;       const f32x4 ov = {v[i].x * rstd * gq.x + bq.x, v[i].y * rstd * gq.y + bq.y, v[i].z * rstd * gq.z + bq.z, v[i].w * rstd * gq.w + bq.w};
.LBB0_1089:
	s_or_b64 exec, exec, s[0:1]
	s_waitcnt lgkmcnt(0)
	s_barrier
	s_movk_i32 s0, 0x2000
	v_ashrrev_i32_e32 v0, 6, v189
	v_add_u32_e32 v0, s52, v0
	v_cmp_gt_i32_e32 vcc, s0, v0
	s_and_saveexec_b64 s[0:1], vcc
	s_cbranch_execz .LBB0_1096
	v_lshlrev_b32_e32 v1, 2, v189
	v_and_b32_e32 v30, 0xfc, v1
	v_mov_b32_e32 v3, 0
	v_lshlrev_b32_e32 v2, 1, v30
	v_or_b32_e32 v32, 0x400, v30
	v_lshl_add_u64 v[4:5], s[92:93], 0, v[2:3]
	v_lshl_add_u64 v[8:9], s[8:9], 0, v[2:3]
	v_lshlrev_b32_e32 v2, 2, v30
	v_or_b32_e32 v34, 0x500, v30
	v_lshl_add_u64 v[10:11], s[86:87], 0, v[2:3]
	v_lshl_add_u64 v[12:13], s[88:89], 0, v[2:3]
	v_lshlrev_b32_e32 v2, 2, v32
	v_and_b32_e32 v1, 15, v189
	v_or_b32_e32 v36, 0x600, v30
	v_lshl_add_u64 v[14:15], s[86:87], 0, v[2:3]
	v_lshl_add_u64 v[16:17], s[88:89], 0, v[2:3]
	v_lshlrev_b32_e32 v2, 2, v34
	v_or_b32_e32 v38, 0x700, v30
	s_mov_b64 s[0:1], 0x17400000
	v_lshlrev_b32_e32 v6, 2, v1
	v_mov_b32_e32 v7, v3
	v_lshl_add_u64 v[18:19], s[86:87], 0, v[2:3]
	v_lshl_add_u64 v[20:21], s[88:89], 0, v[2:3]
	v_lshlrev_b32_e32 v2, 2, v36
	v_lshl_add_u64 v[4:5], v[4:5], 0, s[0:1]
	v_lshl_add_u64 v[6:7], s[92:93], 0, v[6:7]
	s_mov_b64 s[0:1], 0x21700000
	v_lshl_add_u64 v[22:23], s[86:87], 0, v[2:3]
	v_lshl_add_u64 v[24:25], s[88:89], 0, v[2:3]
	v_lshlrev_b32_e32 v2, 2, v38
	v_lshl_add_u64 v[6:7], v[6:7], 0, s[0:1]
	v_lshl_add_u64 v[26:27], s[86:87], 0, v[2:3]
	v_lshl_add_u64 v[28:29], s[88:89], 0, v[2:3]
	s_mov_b64 s[0:1], 0
	s_mov_b32 s2, 0x3f9837f0
	s_mov_b32 s5, 0
	v_lshlrev_b32_e32 v2, 2, v30
	v_lshlrev_b32_e32 v30, 2, v32
	v_lshlrev_b32_e32 v32, 2, v34
	v_lshlrev_b32_e32 v34, 2, v36
	v_mov_b32_e32 v72, 0x3727c5ac
	s_mov_b32 s3, 0x800000
	v_lshlrev_b32_e32 v36, 2, v38
	s_movk_i32 s6, 0x1fff
	v_mov_b32_e32 v73, 0x3a000000
	global_load_dwordx4 v[108:111], v[10:11], off offset:1024
	global_load_dwordx4 v[112:115], v[12:13], off offset:1024
	global_load_dwordx4 v[116:119], v[10:11], off offset:2048
	global_load_dwordx4 v[120:123], v[12:13], off offset:2048
	global_load_dwordx4 v[124:127], v[10:11], off offset:3072
	global_load_dwordx4 v[128:131], v[12:13], off offset:3072
	global_load_dwordx4 v[132:135], v[14:15], off
	global_load_dwordx4 v[136:139], v[16:17], off
	global_load_dwordx4 v[140:143], v[18:19], off
	global_load_dwordx4 v[144:147], v[20:21], off
	global_load_dwordx4 v[148:151], v[22:23], off
	global_load_dwordx4 v[152:155], v[24:25], off
	global_load_dwordx4 v[156:159], v[26:27], off
	global_load_dwordx4 v[160:163], v[28:29], off
	s_waitcnt vmcnt(0)
	s_branch .LBB0_1092
.LBB0_1091:
	v_add_f32_e32 v1, v71, v70
	v_add_f32_e32 v1, v68, v1
	v_add_f32_e32 v31, v67, v66
	v_add_f32_e32 v1, v69, v1
	v_add_f32_e32 v31, v64, v31
	v_add_f32_e32 v1, 0, v1
	v_add_f32_e32 v31, v65, v31
	v_add_f32_e32 v1, v31, v1
	v_add_f32_e32 v31, v63, v62
	v_add_f32_e32 v31, v60, v31
	v_add_f32_e32 v31, v61, v31
	v_add_f32_e32 v1, v31, v1
	v_add_f32_e32 v31, v59, v58
	v_add_f32_e32 v31, v56, v31
	v_pk_add_f32 v[74:75], v[54:55], v[50:51]
	v_add_f32_e32 v31, v57, v31
	v_pk_add_f32 v[74:75], v[48:49], v[74:75]
	v_add_f32_e32 v1, v31, v1
	v_pk_add_f32 v[74:75], v[52:53], v[74:75]
	v_mov_b32_e32 v31, 0
	v_add_f32_e32 v1, v75, v1
	v_add_f32_e32 v1, v74, v1
	v_pk_add_f32 v[74:75], v[46:47], v[42:43]
	v_mov_b32_e32 v100, v51
	v_pk_add_f32 v[74:75], v[40:41], v[74:75]
	v_mov_b32_e32 v101, v55
	v_pk_add_f32 v[74:75], v[44:45], v[74:75]
	v_mov_b32_e32 v51, v54
	v_add_f32_e32 v1, v75, v1
	v_add_f32_e32 v1, v74, v1
	global_load_dwordx4 v[74:77], v[10:11], off
	global_load_dwordx4 v[78:81], v[12:13], off
	v_add_f32_dpp v1, v1, v1 quad_perm:[1,0,3,2] row_mask:0xf bank_mask:0xf bound_ctrl:1
	v_mov_b32_e32 v102, v49
	v_mov_b32_e32 v103, v53
	v_add_f32_dpp v1, v1, v1 quad_perm:[2,3,0,1] row_mask:0xf bank_mask:0xf bound_ctrl:1
	v_mov_b32_e32 v49, v52
	v_mov_b32_e32 v33, v3
	v_add_f32_dpp v1, v1, v1 row_half_mirror row_mask:0xf bank_mask:0xf bound_ctrl:1
	v_mov_b32_e32 v35, v3
	v_add_u32_e32 v0, s60, v0
	v_add_f32_dpp v1, v1, v1 row_mirror row_mask:0xf bank_mask:0xf bound_ctrl:1
	v_mov_b32_e32 v37, v3
	s_nop 0
	v_mov_b32_dpp v31, v1 row_bcast:15 row_mask:0xa bank_mask:0xf
	v_add_f32_e32 v1, v1, v31
	v_mov_b32_e32 v31, 0
	s_nop 1
	v_mov_b32_dpp v31, v1 row_bcast:31 row_mask:0xc bank_mask:0xf
	v_add_f32_e32 v1, v1, v31
	s_nop 0
	v_readlane_b32 s4, v1, 63
	s_nop 1
	v_mul_f32_e32 v82, s4, v73
	v_pk_add_f32 v[70:71], v[70:71], v[82:83] op_sel_hi:[1,0] neg_lo:[0,1] neg_hi:[0,1]
	v_pk_add_f32 v[66:67], v[66:67], v[82:83] op_sel_hi:[1,0] neg_lo:[0,1] neg_hi:[0,1]
	v_pk_mul_f32 v[84:85], v[70:71], v[70:71]
	v_pk_add_f32 v[68:69], v[68:69], v[82:83] op_sel_hi:[1,0] neg_lo:[0,1] neg_hi:[0,1]
	v_pk_mul_f32 v[88:89], v[66:67], v[66:67]
	v_pk_add_f32 v[64:65], v[64:65], v[82:83] op_sel_hi:[1,0] neg_lo:[0,1] neg_hi:[0,1]
	v_pk_mul_f32 v[86:87], v[68:69], v[68:69]
	v_pk_mul_f32 v[90:91], v[64:65], v[64:65]
	v_add_f32_e32 v1, v88, v89
	v_add_f32_e32 v31, v84, v85
	v_pk_add_f32 v[62:63], v[62:63], v[82:83] op_sel_hi:[1,0] neg_lo:[0,1] neg_hi:[0,1]
	v_pk_add_f32 v[100:101], v[100:101], v[82:83] op_sel_hi:[1,0] neg_lo:[0,1] neg_hi:[0,1]
	v_pk_add_f32 v[50:51], v[50:51], v[82:83] op_sel_hi:[1,0] neg_lo:[0,1] neg_hi:[0,1]
	v_add_f32_e32 v1, v90, v1
	v_add_f32_e32 v31, v86, v31
	v_pk_mul_f32 v[92:93], v[62:63], v[62:63]
	v_pk_add_f32 v[60:61], v[60:61], v[82:83] op_sel_hi:[1,0] neg_lo:[0,1] neg_hi:[0,1]
	v_mov_b32_e32 v54, v51
	v_mov_b32_e32 v55, v101
	v_add_f32_e32 v1, v91, v1
	v_add_f32_e32 v31, v87, v31
	v_pk_mul_f32 v[94:95], v[60:61], v[60:61]
	v_pk_add_f32 v[102:103], v[102:103], v[82:83] op_sel_hi:[1,0] neg_lo:[0,1] neg_hi:[0,1]
; DEVINL void phase11(const Params& p) {
;     ...
;     const float mu = allred64(sum) * (1.f / 2048.f);
;     float sq = 0.f;
; #pragma unroll
;     for (int i = 0; i < 8; ++i) {
;       v[i].x -= mu; v[i].y -= mu; v[i].z -= mu; v[i].w -= mu;
;       sq += v[i].x * v[i].x + v[i].y * v[i].y + v[i].z * v[i].z + v[i].w * v[i].w;
;     }
;     const float rstd = rsqrtf(allred64(sq) * (1.f / 2048.f) + 1e-5f);
; #pragma unroll
;     for (int i = 0; i < 8; ++i) {
;       const int c = i * 256 + lane * 4;
;       float4 gq = *(const float4*)(p.ln2_g + c);
;       float4 bq = *(const float4*)(p.ln2_b + c);
;       const f32x4 ov = {v[i].x * rstd * gq.x + bq.x, v[i].y * rstd * gq.y + bq.y, v[i].z * rstd * gq.z + bq.z, v[i].w * rstd * gq.w + bq.w};
;       __builtin_nontemporal_store(ov, (f32x4*)(p.out + (long)row * 2048 + c));
;     }
	v_pk_add_f32 v[48:49], v[48:49], v[82:83] op_sel_hi:[1,0] neg_lo:[0,1] neg_hi:[0,1]
	v_mov_b32_e32 v52, v50
	v_mov_b32_e32 v53, v100
	v_pk_mul_f32 v[54:55], v[54:55], v[54:55]
	v_add_f32_e32 v1, v31, v1
	v_add_f32_e32 v31, v92, v93
	v_pk_add_f32 v[58:59], v[58:59], v[82:83] op_sel_hi:[1,0] neg_lo:[0,1] neg_hi:[0,1]
	v_pk_fma_f32 v[52:53], v[52:53], v[52:53], v[54:55]
	v_mov_b32_e32 v54, v48
	v_mov_b32_e32 v55, v102
	v_add_f32_e32 v31, v94, v31
	v_pk_mul_f32 v[96:97], v[58:59], v[58:59]
	v_pk_add_f32 v[56:57], v[56:57], v[82:83] op_sel_hi:[1,0] neg_lo:[0,1] neg_hi:[0,1]
	v_pk_fma_f32 v[52:53], v[54:55], v[54:55], v[52:53]
	v_mov_b32_e32 v54, v43
	v_mov_b32_e32 v55, v47
	v_mov_b32_e32 v43, v46
	v_add_f32_e32 v31, v95, v31
	v_pk_mul_f32 v[98:99], v[56:57], v[56:57]
	v_mov_b32_e32 v104, v49
	v_mov_b32_e32 v105, v103
	v_pk_add_f32 v[54:55], v[54:55], v[82:83] op_sel_hi:[1,0] neg_lo:[0,1] neg_hi:[0,1]
	v_pk_add_f32 v[46:47], v[42:43], v[82:83] op_sel_hi:[1,0] neg_lo:[0,1] neg_hi:[0,1]
	v_add_f32_e32 v1, v31, v1
	v_add_f32_e32 v31, v96, v97
	v_pk_fma_f32 v[52:53], v[104:105], v[104:105], v[52:53]
	v_mov_b32_e32 v104, v41
	v_mov_b32_e32 v105, v45
	v_mov_b32_e32 v41, v44
	v_mov_b32_e32 v42, v47
	v_mov_b32_e32 v43, v55
	v_add_f32_e32 v31, v98, v31
	v_pk_add_f32 v[104:105], v[104:105], v[82:83] op_sel_hi:[1,0] neg_lo:[0,1] neg_hi:[0,1]
	v_pk_add_f32 v[82:83], v[40:41], v[82:83] op_sel_hi:[1,0] neg_lo:[0,1] neg_hi:[0,1]
	v_mov_b32_e32 v40, v46
	v_mov_b32_e32 v41, v54
	v_pk_mul_f32 v[42:43], v[42:43], v[42:43]
	v_add_f32_e32 v31, v99, v31
	v_pk_fma_f32 v[40:41], v[40:41], v[40:41], v[42:43]
	v_mov_b32_e32 v42, v82
	v_mov_b32_e32 v43, v104
	v_add_f32_e32 v1, v31, v1
	v_mov_b32_e32 v44, v83
	v_mov_b32_e32 v45, v105
	v_pk_fma_f32 v[40:41], v[42:43], v[42:43], v[40:41]
	v_add_f32_e32 v1, v53, v1
	v_pk_fma_f32 v[40:41], v[44:45], v[44:45], v[40:41]
	v_add_f32_e32 v1, v52, v1
	v_add_f32_e32 v1, v41, v1
	v_add_f32_e32 v1, v40, v1
	v_mov_b32_e32 v31, v3
	v_lshl_add_u64 v[52:53], v[38:39], 2, s[90:91]
	v_add_f32_dpp v1, v1, v1 quad_perm:[1,0,3,2] row_mask:0xf bank_mask:0xf bound_ctrl:1
	v_lshl_add_u64 v[84:85], v[52:53], 0, v[2:3]
	s_nop 0
	v_add_f32_dpp v1, v1, v1 quad_perm:[2,3,0,1] row_mask:0xf bank_mask:0xf bound_ctrl:1
	s_nop 1
	v_add_f32_dpp v1, v1, v1 row_half_mirror row_mask:0xf bank_mask:0xf bound_ctrl:1
	s_nop 1
	v_add_f32_dpp v1, v1, v1 row_mirror row_mask:0xf bank_mask:0xf bound_ctrl:1
	s_nop 1
	v_mov_b32_dpp v31, v1 row_bcast:15 row_mask:0xa bank_mask:0xf
	v_add_f32_e32 v1, v1, v31
	v_mov_b32_e32 v31, v3
	s_nop 1
	v_mov_b32_dpp v31, v1 row_bcast:31 row_mask:0xc bank_mask:0xf
	v_add_f32_e32 v1, v1, v31
	s_nop 0
	v_readlane_b32 s4, v1, 63
	s_nop 1
	v_fma_f32 v1, s4, v73, v72
	v_mul_f32_e32 v31, 0x4b800000, v1
	v_cmp_gt_f32_e32 vcc, s3, v1
	s_nop 1
	v_cndmask_b32_e32 v1, v1, v31, vcc
	v_rsq_f32_e32 v1, v1
	s_nop 0
	v_mul_f32_e32 v31, 0x45800000, v1
	v_cndmask_b32_e32 v86, v1, v31, vcc
	v_pk_mul_f32 v[38:39], v[70:71], v[86:87] op_sel_hi:[1,0]
	v_pk_mul_f32 v[40:41], v[68:69], v[86:87] op_sel_hi:[1,0]
	s_waitcnt vmcnt(0)
	v_pk_fma_f32 v[38:39], v[74:75], v[38:39], v[78:79]
	v_pk_fma_f32 v[40:41], v[76:77], v[40:41], v[80:81]
	global_store_dwordx4 v[84:85], v[38:41], off nt
	v_pk_mul_f32 v[64:65], v[64:65], v[86:87] op_sel_hi:[1,0]
	v_pk_mul_f32 v[66:67], v[66:67], v[86:87] op_sel_hi:[1,0]
	v_pk_mul_f32 v[60:61], v[60:61], v[86:87] op_sel_hi:[1,0]
	v_pk_mul_f32 v[62:63], v[62:63], v[86:87] op_sel_hi:[1,0]
	v_pk_mul_f32 v[56:57], v[56:57], v[86:87] op_sel_hi:[1,0]
	v_pk_mul_f32 v[58:59], v[58:59], v[86:87] op_sel_hi:[1,0]
	v_mov_b32_e32 v31, v3
	v_pk_mul_f32 v[48:49], v[48:49], v[86:87] op_sel_hi:[1,0]
	v_pk_mul_f32 v[50:51], v[50:51], v[86:87] op_sel_hi:[1,0]
	v_pk_mul_f32 v[54:55], v[54:55], v[86:87] op_sel_hi:[1,0]
	v_cmp_lt_i32_e32 vcc, s6, v0
	v_pk_mul_f32 v[46:47], v[46:47], v[86:87] op_sel_hi:[1,0]
	s_or_b64 s[0:1], vcc, s[0:1]
	v_pk_fma_f32 v[42:43], v[66:67], v[108:109], v[112:113]
	v_pk_fma_f32 v[44:45], v[64:65], v[110:111], v[114:115]
	global_store_dwordx4 v[84:85], v[42:45], off offset:1024 nt
	v_pk_fma_f32 v[38:39], v[62:63], v[116:117], v[120:121]
	v_pk_fma_f32 v[40:41], v[60:61], v[118:119], v[122:123]
	global_store_dwordx4 v[84:85], v[38:41], off offset:2048 nt
	v_pk_mul_f32 v[60:61], v[100:101], v[86:87] op_sel_hi:[1,0]
	v_pk_fma_f32 v[42:43], v[58:59], v[124:125], v[128:129]
	v_pk_fma_f32 v[44:45], v[56:57], v[126:127], v[130:131]
	global_store_dwordx4 v[84:85], v[42:45], off offset:3072 nt
	v_pk_mul_f32 v[58:59], v[102:103], v[86:87] op_sel_hi:[1,0]
	v_lshl_add_u64 v[56:57], v[52:53], 0, v[30:31]
	v_pk_fma_f32 v[38:39], v[60:61], v[132:133], v[136:137]
	v_pk_fma_f32 v[40:41], v[58:59], v[134:135], v[138:139]
	global_store_dwordx4 v[56:57], v[38:41], off nt
	v_lshl_add_u64 v[56:57], v[52:53], 0, v[32:33]
	v_pk_fma_f32 v[42:43], v[50:51], v[140:141], v[144:145]
	v_pk_fma_f32 v[44:45], v[48:49], v[142:143], v[146:147]
	global_store_dwordx4 v[56:57], v[42:45], off nt
	v_pk_mul_f32 v[50:51], v[104:105], v[86:87] op_sel_hi:[1,0]
	v_lshl_add_u64 v[48:49], v[52:53], 0, v[34:35]
	v_pk_fma_f32 v[38:39], v[54:55], v[148:149], v[152:153]
	v_pk_fma_f32 v[40:41], v[50:51], v[150:151], v[154:155]
	global_store_dwordx4 v[48:49], v[38:41], off nt
	v_pk_mul_f32 v[50:51], v[82:83], v[86:87] op_sel_hi:[1,0]
	v_lshl_add_u64 v[48:49], v[52:53], 0, v[36:37]
	v_pk_fma_f32 v[42:43], v[46:47], v[156:157], v[160:161]
	v_pk_fma_f32 v[44:45], v[50:51], v[158:159], v[162:163]
	global_store_dwordx4 v[48:49], v[42:45], off nt
	s_andn2_b64 exec, exec, s[0:1]
	s_cbranch_execz .LBB0_1096
